# code placement pads before all five GEMM K-loops (loop alignment tuned); sample-row GEMM loads pipelined; relu2 epilogue scale loads hoisted
# speedup vs baseline: 1.0049x; 1.0020x over previous
; template <class Epi, class Sched, bool ALIGN_EPI = false, bool SP2 = false>
; __device__ __forceinline__ void gemm_phase(PG8_LAS unsigned char* lds, const Gemm g, const Sched& S, const Epi& E) {
;     ...
;         const bool has_next = S.next(ui + 1, nxt);
;         const char* nA = has_next ? (const char*)g.A + (size_t)nxt.pm * tstep : cA; const char* nB = has_next ? (const char*)g.Bt + (size_t)nxt.pn * tstep : cB;
;         for (int t = 0; t < nt; t += 2) {
;     ...
; #pragma unroll
;         for (int a = 0; a < 2; ++a)
; #pragma unroll
;             for (int b = 0; b < 2; ++b)
; #pragma unroll
;                 for (int m = 0; m < 4; ++m)
; #pragma unroll
;                     for (int n = 0; n < 2; ++n) acc[a][b][m][n] = (f32x4){0.f, 0.f, 0.f, 0.f};
;         cur = nxt; cA = nA; cB = nB; ++ui;
.LBB0_220:
	s_ashr_i32 s25, s24, 31
	s_lshl_b64 s[2:3], s[24:25], 20
	s_add_u32 s2, s12, s2
	s_addc_u32 s3, s13, s3
	s_and_b64 s[26:27], s[8:9], exec
	s_cselect_b32 s25, s3, s1
	s_cselect_b32 s46, s2, s0
	s_ashr_i32 s23, s22, 31
	s_lshl_b64 s[26:27], s[22:23], 20
	s_add_u32 s26, s31, s26
	s_addc_u32 s27, s34, s27
	s_and_b64 s[28:29], s[8:9], exec
	s_cselect_b32 s23, s27, s5
	s_cselect_b32 s47, s26, s4
	s_add_u32 s0, s0, 0x80080
	s_addc_u32 s1, s1, 0
	s_add_u32 s48, s4, 0x100
	v_mov_b32_e32 v0, 0
	s_addc_u32 s49, s5, 0
	s_mov_b32 s50, -2
	v_mov_b32_e32 v1, v0
	s_waitcnt lgkmcnt(0)
	v_mov_b32_e32 v2, v0
	v_mov_b32_e32 v3, v0
	v_mov_b32_e32 v4, v0
	v_mov_b32_e32 v5, v0
	v_mov_b32_e32 v6, v0
	v_mov_b32_e32 v7, v0
	v_mov_b32_e32 v16, v0
	v_mov_b32_e32 v17, v0
	s_waitcnt vmcnt(0)
	v_mov_b32_e32 v18, v0
	v_mov_b32_e32 v19, v0
	v_mov_b32_e32 v20, v0
	v_mov_b32_e32 v21, v0
	v_mov_b32_e32 v22, v0
	v_mov_b32_e32 v23, v0
	v_mov_b32_e32 v32, v0
	v_mov_b32_e32 v33, v0
	v_mov_b32_e32 v34, v0
	v_mov_b32_e32 v35, v0
	v_mov_b32_e32 v36, v0
	v_mov_b32_e32 v37, v0
	v_mov_b32_e32 v38, v0
	v_mov_b32_e32 v39, v0
	v_mov_b32_e32 v48, v0
	v_mov_b32_e32 v49, v0
	v_mov_b32_e32 v50, v0
	v_mov_b32_e32 v51, v0
	v_mov_b32_e32 v52, v0
	v_mov_b32_e32 v53, v0
	v_mov_b32_e32 v54, v0
	v_mov_b32_e32 v55, v0
	v_mov_b32_e32 v8, v0
	v_mov_b32_e32 v9, v0
	v_mov_b32_e32 v10, v0
	v_mov_b32_e32 v11, v0
	v_mov_b32_e32 v12, v0
	v_mov_b32_e32 v13, v0
	v_mov_b32_e32 v14, v0
	v_mov_b32_e32 v15, v0
	v_mov_b32_e32 v24, v0
	v_mov_b32_e32 v25, v0
	v_mov_b32_e32 v26, v0
	v_mov_b32_e32 v27, v0
	v_mov_b32_e32 v28, v0
	v_mov_b32_e32 v29, v0
	v_mov_b32_e32 v30, v0
	v_mov_b32_e32 v31, v0
	v_mov_b32_e32 v40, v0
	v_mov_b32_e32 v41, v0
	v_mov_b32_e32 v42, v0
	v_mov_b32_e32 v43, v0
	v_mov_b32_e32 v44, v0
	v_mov_b32_e32 v45, v0
	v_mov_b32_e32 v46, v0
	v_mov_b32_e32 v47, v0
	v_mov_b32_e32 v56, v0
	v_mov_b32_e32 v57, v0
	v_mov_b32_e32 v58, v0
	v_mov_b32_e32 v59, v0
	v_mov_b32_e32 v60, v0
	v_mov_b32_e32 v61, v0
	v_mov_b32_e32 v62, v0
	v_mov_b32_e32 v63, v0
	v_mov_b32_e32 v64, v0
	v_mov_b32_e32 v65, v0
	v_mov_b32_e32 v66, v0
	v_mov_b32_e32 v67, v0
	v_mov_b32_e32 v68, v0
	v_mov_b32_e32 v69, v0
	v_mov_b32_e32 v70, v0
	v_mov_b32_e32 v71, v0
	v_mov_b32_e32 v80, v0
	v_mov_b32_e32 v81, v0
	v_mov_b32_e32 v82, v0
	v_mov_b32_e32 v83, v0
	v_mov_b32_e32 v84, v0
	v_mov_b32_e32 v85, v0
	v_mov_b32_e32 v86, v0
	v_mov_b32_e32 v87, v0
	v_mov_b32_e32 v96, v0
	v_mov_b32_e32 v97, v0
	v_mov_b32_e32 v98, v0
	v_mov_b32_e32 v99, v0
	v_mov_b32_e32 v100, v0
	v_mov_b32_e32 v101, v0
	v_mov_b32_e32 v102, v0
	v_mov_b32_e32 v103, v0
	v_mov_b32_e32 v112, v0
	v_mov_b32_e32 v113, v0
	v_mov_b32_e32 v114, v0
	v_mov_b32_e32 v115, v0
	v_mov_b32_e32 v116, v0
	v_mov_b32_e32 v117, v0
	v_mov_b32_e32 v118, v0
	v_mov_b32_e32 v119, v0
	v_mov_b32_e32 v72, v0
	v_mov_b32_e32 v73, v0
	v_mov_b32_e32 v74, v0
	v_mov_b32_e32 v75, v0
	v_mov_b32_e32 v76, v0
	v_mov_b32_e32 v77, v0
	v_mov_b32_e32 v78, v0
	v_mov_b32_e32 v79, v0
	v_mov_b32_e32 v88, v0
	v_mov_b32_e32 v89, v0
	v_mov_b32_e32 v90, v0
	v_mov_b32_e32 v91, v0
	v_mov_b32_e32 v92, v0
	v_mov_b32_e32 v93, v0
	v_mov_b32_e32 v94, v0
	v_mov_b32_e32 v95, v0
	v_mov_b32_e32 v104, v0
	v_mov_b32_e32 v105, v0
	v_mov_b32_e32 v106, v0
	v_mov_b32_e32 v107, v0
	v_mov_b32_e32 v108, v0
	v_mov_b32_e32 v109, v0
	v_mov_b32_e32 v110, v0
	v_mov_b32_e32 v111, v0
	v_mov_b32_e32 v120, v0
	v_mov_b32_e32 v121, v0
	v_mov_b32_e32 v122, v0
	v_mov_b32_e32 v123, v0
	v_mov_b32_e32 v124, v0
	v_mov_b32_e32 v125, v0
	v_mov_b32_e32 v126, v0
	v_mov_b32_e32 v127, v0
	s_nop 0
	s_nop 0
	s_nop 0
	s_nop 0
	s_nop 0
	s_nop 0
	s_nop 0
	s_nop 0
	s_nop 0
	s_nop 0
	s_nop 0
	s_nop 0
	s_nop 0
	s_nop 0
	s_nop 0

; template <class Epi, class Sched, bool ALIGN_EPI = false, bool SP2 = false>
; __device__ __forceinline__ void gemm_phase(PG8_LAS unsigned char* lds, const Gemm g, const Sched& S, const Epi& E) {
;     ...
;         const bool has_next = S.next(ui + 1, nxt);
;         const char* nA = has_next ? (const char*)g.A + (size_t)nxt.pm * tstep : cA; const char* nB = has_next ? (const char*)g.Bt + (size_t)nxt.pn * tstep : cB;
;         for (int t = 0; t < nt; t += 2) {
;     ...
; #pragma unroll
;         for (int a = 0; a < 2; ++a)
; #pragma unroll
;             for (int b = 0; b < 2; ++b)
; #pragma unroll
;                 for (int m = 0; m < 4; ++m)
; #pragma unroll
;                     for (int n = 0; n < 2; ++n) acc[a][b][m][n] = (f32x4){0.f, 0.f, 0.f, 0.f};
;         cur = nxt; cA = nA; cB = nB; ++ui;
.LBB0_446:
	s_ashr_i32 s49, s48, 31
	s_lshl_b64 s[8:9], s[48:49], 20
	s_add_u32 s50, s62, s8
	s_addc_u32 s51, s63, s9
	s_and_b64 s[8:9], s[6:7], exec
	s_cselect_b32 s3, s51, s1
	s_cselect_b32 s33, s50, s0
	s_ashr_i32 s47, s46, 31
	s_lshl_b64 s[8:9], s[46:47], 20
	s_add_u32 s52, s64, s8
	s_addc_u32 s53, s65, s9
	s_and_b64 s[8:9], s[6:7], exec
	s_cselect_b32 s47, s53, s5
	s_cselect_b32 s49, s52, s4
	s_add_u32 s0, s0, 0x80080
	s_addc_u32 s1, s1, 0
	s_add_u32 s56, s4, 0x100
	s_waitcnt vmcnt(0)
	v_mov_b32_e32 v32, 0
	s_addc_u32 s57, s5, 0
	s_mov_b32 s58, -2
	v_mov_b32_e32 v33, v32
	v_mov_b32_e32 v34, v32
	v_mov_b32_e32 v35, v32
	v_mov_b32_e32 v36, v32
	v_mov_b32_e32 v37, v32
	v_mov_b32_e32 v38, v32
	v_mov_b32_e32 v39, v32
	v_mov_b32_e32 v48, v32
	v_mov_b32_e32 v49, v32
	v_mov_b32_e32 v50, v32
	v_mov_b32_e32 v51, v32
	v_mov_b32_e32 v52, v32
	v_mov_b32_e32 v53, v32
	v_mov_b32_e32 v54, v32
	v_mov_b32_e32 v55, v32
	v_mov_b32_e32 v64, v32
	v_mov_b32_e32 v65, v32
	v_mov_b32_e32 v66, v32
	v_mov_b32_e32 v67, v32
	v_mov_b32_e32 v68, v32
	v_mov_b32_e32 v69, v32
	v_mov_b32_e32 v70, v32
	v_mov_b32_e32 v71, v32
	v_mov_b32_e32 v80, v32
	v_mov_b32_e32 v81, v32
	v_mov_b32_e32 v82, v32
	v_mov_b32_e32 v83, v32
	v_mov_b32_e32 v84, v32
	v_mov_b32_e32 v85, v32
	v_mov_b32_e32 v86, v32
	v_mov_b32_e32 v87, v32
	v_mov_b32_e32 v40, v32
	v_mov_b32_e32 v41, v32
	v_mov_b32_e32 v42, v32
	v_mov_b32_e32 v43, v32
	v_mov_b32_e32 v44, v32
	v_mov_b32_e32 v45, v32
	v_mov_b32_e32 v46, v32
	v_mov_b32_e32 v47, v32
	v_mov_b32_e32 v56, v32
	v_mov_b32_e32 v57, v32
	v_mov_b32_e32 v58, v32
	v_mov_b32_e32 v59, v32
	v_mov_b32_e32 v60, v32
	v_mov_b32_e32 v61, v32
	v_mov_b32_e32 v62, v32
	v_mov_b32_e32 v63, v32
	v_mov_b32_e32 v72, v32
	v_mov_b32_e32 v73, v32
	v_mov_b32_e32 v74, v32
	v_mov_b32_e32 v75, v32
	v_mov_b32_e32 v76, v32
	v_mov_b32_e32 v77, v32
	v_mov_b32_e32 v78, v32
	v_mov_b32_e32 v79, v32
	v_mov_b32_e32 v88, v32
	v_mov_b32_e32 v89, v32
	v_mov_b32_e32 v90, v32
	v_mov_b32_e32 v91, v32
	v_mov_b32_e32 v92, v32
	v_mov_b32_e32 v93, v32
	v_mov_b32_e32 v94, v32
	v_mov_b32_e32 v95, v32
	v_mov_b32_e32 v96, v32
	v_mov_b32_e32 v97, v32
	v_mov_b32_e32 v98, v32
	v_mov_b32_e32 v99, v32
	v_mov_b32_e32 v100, v32
	v_mov_b32_e32 v101, v32
	v_mov_b32_e32 v102, v32
	v_mov_b32_e32 v103, v32
	v_mov_b32_e32 v112, v32
	v_mov_b32_e32 v113, v32
	v_mov_b32_e32 v114, v32
	v_mov_b32_e32 v115, v32
	v_mov_b32_e32 v116, v32
	v_mov_b32_e32 v117, v32
	v_mov_b32_e32 v118, v32
	v_mov_b32_e32 v119, v32
	v_mov_b32_e32 v0, v32
	v_mov_b32_e32 v1, v32
	v_mov_b32_e32 v2, v32
	v_mov_b32_e32 v3, v32
	v_mov_b32_e32 v4, v32
	v_mov_b32_e32 v5, v32
	v_mov_b32_e32 v6, v32
	v_mov_b32_e32 v7, v32
	v_mov_b32_e32 v16, v32
	v_mov_b32_e32 v17, v32
	v_mov_b32_e32 v18, v32
	v_mov_b32_e32 v19, v32
	v_mov_b32_e32 v20, v32
	v_mov_b32_e32 v21, v32
	v_mov_b32_e32 v22, v32
	v_mov_b32_e32 v23, v32
	v_mov_b32_e32 v104, v32
	v_mov_b32_e32 v105, v32
	v_mov_b32_e32 v106, v32
	v_mov_b32_e32 v107, v32
	v_mov_b32_e32 v108, v32
	v_mov_b32_e32 v109, v32
	v_mov_b32_e32 v110, v32
	v_mov_b32_e32 v111, v32
	v_mov_b32_e32 v120, v32
	v_mov_b32_e32 v121, v32
	v_mov_b32_e32 v122, v32
	v_mov_b32_e32 v123, v32
	v_mov_b32_e32 v124, v32
	v_mov_b32_e32 v125, v32
	v_mov_b32_e32 v126, v32
	v_mov_b32_e32 v127, v32
	v_mov_b32_e32 v8, v32
	v_mov_b32_e32 v9, v32
	v_mov_b32_e32 v10, v32
	v_mov_b32_e32 v11, v32
	v_mov_b32_e32 v12, v32
	v_mov_b32_e32 v13, v32
	v_mov_b32_e32 v14, v32
	v_mov_b32_e32 v15, v32
	v_mov_b32_e32 v24, v32
	v_mov_b32_e32 v25, v32
	v_mov_b32_e32 v26, v32
	v_mov_b32_e32 v27, v32
	v_mov_b32_e32 v28, v32
	v_mov_b32_e32 v29, v32
	v_mov_b32_e32 v30, v32
	v_mov_b32_e32 v31, v32
	s_mov_b64 vcc, 0x80
	s_nop 0

; template <class Epi, class Sched, bool ALIGN_EPI = false, bool SP2 = false>
; __device__ __forceinline__ void gemm_phase(PG8_LAS unsigned char* lds, const Gemm g, const Sched& S, const Epi& E) {
;     ...
;         const bool has_next = S.next(ui + 1, nxt);
;         const char* nA = has_next ? (const char*)g.A + (size_t)nxt.pm * tstep : cA; const char* nB = has_next ? (const char*)g.Bt + (size_t)nxt.pn * tstep : cB;
;         for (int t = 0; t < nt; t += 2) {
.LBB0_882:
	s_add_u32 s45, s24, 0x100
	s_addc_u32 s46, s25, 0
	s_ashr_i32 s19, s18, 31
	s_lshl_b64 s[20:21], s[18:19], 20
	s_add_u32 s22, s30, s20
	s_addc_u32 s23, s31, s21
	s_and_b64 s[20:21], s[4:5], exec
	s_cselect_b32 s19, s23, s15
	s_cselect_b32 s47, s22, s14
	s_ashr_i32 s17, s16, 31
	s_lshl_b64 s[20:21], s[16:17], 20
	s_add_u32 s20, s8, s20
	s_addc_u32 s21, s9, s21
	s_and_b64 s[26:27], s[4:5], exec
	s_cselect_b32 s17, s21, s25
	s_cselect_b32 s48, s20, s24
	s_add_u32 s24, s14, 0x80080
	s_addc_u32 s25, s15, 0
	v_lshl_add_u64 v[46:47], s[24:25], 0, v[42:43]
	v_lshl_add_u64 v[48:49], s[24:25], 0, v[44:45]
	s_mov_b32 s49, -2
	s_mov_b64 s[24:25], 0
	s_nop 0
	s_nop 0

; template <class Epi, class Sched, bool ALIGN_EPI = false, bool SP2 = false>
; __device__ __forceinline__ void gemm_phase(PG8_LAS unsigned char* lds, const Gemm g, const Sched& S, const Epi& E) {
;     ...
;         const bool has_next = S.next(ui + 1, nxt);
;         const char* nA = has_next ? (const char*)g.A + (size_t)nxt.pm * tstep : cA; const char* nB = has_next ? (const char*)g.Bt + (size_t)nxt.pn * tstep : cB;
;         for (int t = 0; t < nt; t += 2) {
;     ...
; #pragma unroll
;         for (int a = 0; a < 2; ++a)
; #pragma unroll
;             for (int b = 0; b < 2; ++b)
; #pragma unroll
;                 for (int m = 0; m < 4; ++m)
; #pragma unroll
;                     for (int n = 0; n < 2; ++n) acc[a][b][m][n] = (f32x4){0.f, 0.f, 0.f, 0.f};
;         cur = nxt; cA = nA; cB = nB; ++ui;
.LBB0_1057:
	s_ashr_i32 s21, s20, 31
	s_lshl_b64 s[22:23], s[20:21], 20
	s_add_u32 s22, s12, s22
	s_addc_u32 s23, s13, s23
	s_and_b64 s[24:25], s[0:1], exec
	s_cselect_b32 s21, s23, s27
	s_cselect_b32 s47, s22, s26
	s_ashr_i32 s19, s18, 31
	s_lshl_b64 s[24:25], s[18:19], 20
	s_add_u32 s24, s33, s24
	s_addc_u32 s25, s34, s25
	s_and_b64 s[30:31], s[0:1], exec
	s_cselect_b32 s19, s25, s29
	s_cselect_b32 s48, s24, s28
	s_add_u32 s26, s26, 0x80080
	s_addc_u32 s27, s27, 0
	s_add_u32 s49, s28, 0x100
	v_mov_b32_e32 v0, 0
	s_addc_u32 s50, s29, 0
	s_mov_b32 s51, -2
	v_mov_b32_e32 v1, v0
	v_mov_b32_e32 v2, v0
	v_mov_b32_e32 v3, v0
	v_mov_b32_e32 v4, v0
	v_mov_b32_e32 v5, v0
	v_mov_b32_e32 v6, v0
	v_mov_b32_e32 v7, v0
	v_mov_b32_e32 v16, v0
	v_mov_b32_e32 v17, v0
	v_mov_b32_e32 v18, v0
	v_mov_b32_e32 v19, v0
	v_mov_b32_e32 v20, v0
	v_mov_b32_e32 v21, v0
	v_mov_b32_e32 v22, v0
	v_mov_b32_e32 v23, v0
	v_mov_b32_e32 v32, v0
	v_mov_b32_e32 v33, v0
	v_mov_b32_e32 v34, v0
	v_mov_b32_e32 v35, v0
	v_mov_b32_e32 v36, v0
	v_mov_b32_e32 v37, v0
	v_mov_b32_e32 v38, v0
	v_mov_b32_e32 v39, v0
	v_mov_b32_e32 v48, v0
	v_mov_b32_e32 v49, v0
	v_mov_b32_e32 v50, v0
	v_mov_b32_e32 v51, v0
	v_mov_b32_e32 v52, v0
	v_mov_b32_e32 v53, v0
	v_mov_b32_e32 v54, v0
	v_mov_b32_e32 v55, v0
	v_mov_b32_e32 v8, v0
	v_mov_b32_e32 v9, v0
	v_mov_b32_e32 v10, v0
	v_mov_b32_e32 v11, v0
	v_mov_b32_e32 v12, v0
	v_mov_b32_e32 v13, v0
	v_mov_b32_e32 v14, v0
	v_mov_b32_e32 v15, v0
	v_mov_b32_e32 v24, v0
	v_mov_b32_e32 v25, v0
	v_mov_b32_e32 v26, v0
	v_mov_b32_e32 v27, v0
	v_mov_b32_e32 v28, v0
	v_mov_b32_e32 v29, v0
	v_mov_b32_e32 v30, v0
	v_mov_b32_e32 v31, v0
	v_mov_b32_e32 v40, v0
	v_mov_b32_e32 v41, v0
	v_mov_b32_e32 v42, v0
	v_mov_b32_e32 v43, v0
	v_mov_b32_e32 v44, v0
	v_mov_b32_e32 v45, v0
	v_mov_b32_e32 v46, v0
	v_mov_b32_e32 v47, v0
	v_mov_b32_e32 v56, v0
	v_mov_b32_e32 v57, v0
	v_mov_b32_e32 v58, v0
	v_mov_b32_e32 v59, v0
	v_mov_b32_e32 v60, v0
	v_mov_b32_e32 v61, v0
	v_mov_b32_e32 v62, v0
	v_mov_b32_e32 v63, v0
	v_mov_b32_e32 v64, v0
	v_mov_b32_e32 v65, v0
	v_mov_b32_e32 v66, v0
	v_mov_b32_e32 v67, v0
	v_mov_b32_e32 v68, v0
	v_mov_b32_e32 v69, v0
	v_mov_b32_e32 v70, v0
	v_mov_b32_e32 v71, v0
	v_mov_b32_e32 v80, v0
	v_mov_b32_e32 v81, v0
	v_mov_b32_e32 v82, v0
	v_mov_b32_e32 v83, v0
	v_mov_b32_e32 v84, v0
	v_mov_b32_e32 v85, v0
	v_mov_b32_e32 v86, v0
	v_mov_b32_e32 v87, v0
	v_mov_b32_e32 v96, v0
	v_mov_b32_e32 v97, v0
	v_mov_b32_e32 v98, v0
	v_mov_b32_e32 v99, v0
	v_mov_b32_e32 v100, v0
	v_mov_b32_e32 v101, v0
	v_mov_b32_e32 v102, v0
	v_mov_b32_e32 v103, v0
	v_mov_b32_e32 v112, v0
	v_mov_b32_e32 v113, v0
	v_mov_b32_e32 v114, v0
	v_mov_b32_e32 v115, v0
	v_mov_b32_e32 v116, v0
	v_mov_b32_e32 v117, v0
	v_mov_b32_e32 v118, v0
	v_mov_b32_e32 v119, v0
	v_mov_b32_e32 v72, v0
	v_mov_b32_e32 v73, v0
	v_mov_b32_e32 v74, v0
	v_mov_b32_e32 v75, v0
	v_mov_b32_e32 v76, v0
	v_mov_b32_e32 v77, v0
	v_mov_b32_e32 v78, v0
	v_mov_b32_e32 v79, v0
	v_mov_b32_e32 v88, v0
	v_mov_b32_e32 v89, v0
	v_mov_b32_e32 v90, v0
	v_mov_b32_e32 v91, v0
	v_mov_b32_e32 v92, v0
	v_mov_b32_e32 v93, v0
	v_mov_b32_e32 v94, v0
	v_mov_b32_e32 v95, v0
	v_mov_b32_e32 v104, v0
	v_mov_b32_e32 v105, v0
	v_mov_b32_e32 v106, v0
	v_mov_b32_e32 v107, v0
	v_mov_b32_e32 v108, v0
	v_mov_b32_e32 v109, v0
	v_mov_b32_e32 v110, v0
	v_mov_b32_e32 v111, v0
	v_mov_b32_e32 v120, v0
	v_mov_b32_e32 v121, v0
	v_mov_b32_e32 v122, v0
	v_mov_b32_e32 v123, v0
	v_mov_b32_e32 v124, v0
	v_mov_b32_e32 v125, v0
	v_mov_b32_e32 v126, v0
	v_mov_b32_e32 v127, v0
	s_nop 0
	s_nop 0
	s_nop 0
	s_nop 0
	s_nop 0
	s_nop 0
	s_nop 0
	s_nop 0
	s_nop 0
	s_nop 0
	s_nop 0
	s_nop 0
	s_nop 0
	s_nop 0
	s_nop 0
	s_nop 0
